# MLA tile loop: waves 4-7 start each tile 192 cycles late (s_sleep 3) to de-synchronise the two waves of a SIMD
# baseline (speedup 1.0000x reference)
.LBB0_1385:
	s_cmp_gt_i32 s21, s17
	s_cbranch_scc1 .LBB0_1391
	s_cmp_lt_u32 s14, 2
	s_cbranch_scc1 .Lmla_nostagger
	s_sleep 3
.Lmla_nostagger:
	s_bitcmp1_b32 s21, 0
	s_cselect_b32 s19, 0xa000, 0
	s_add_i32 s19, s19, 0
	ds_read_b128 v[104:107], v232
	ds_read_b128 v[108:111], v232 offset:1024
	ds_read_b128 v[112:115], v232 offset:2048
	ds_read_b128 v[116:119], v232 offset:3072
	v_add_u32_e32 v120, s19, v165
	v_add_u32_e32 v237, s19, v223
	v_add_u32_e32 v156, v120, v227
	v_add_u32_e32 v158, v120, v229
	v_add_u32_e32 v235, v237, v222
	v_add_u32_e32 v242, s19, v224
	v_add_u32_e32 v157, v120, v228
	ds_read_b128 v[96:99], v156
	ds_read_b128 v[100:103], v157
	v_add_u32_e32 v159, v120, v230
	ds_read_b128 v[120:123], v158
	ds_read_b128 v[124:127], v159
	v_add_u32_e32 v236, v242, v222
	ds_read_b128 v[128:131], v235 offset:16384
	ds_read_b128 v[132:135], v236 offset:16384
	s_setprio 1
	v_xor_b32_e32 v136, 0x80000000, v234
	v_xor_b32_e32 v140, 0x80000000, v233
	v_mov_b32_e32 v137, v136
	v_mov_b32_e32 v138, v136
	v_mov_b32_e32 v139, v136
	v_mov_b32_e32 v141, v140
	v_mov_b32_e32 v142, v140
	v_mov_b32_e32 v143, v140
	s_waitcnt lgkmcnt(0)
	v_mfma_f32_16x16x32_bf16 v[144:147], v[96:99], v[40:43], v[136:139]
	v_mfma_f32_16x16x32_bf16 v[96:99], v[96:99], v[56:59], v[140:143]
	v_mfma_f32_16x16x32_bf16 v[144:147], v[100:103], v[44:47], v[144:147]
	v_mfma_f32_16x16x32_bf16 v[96:99], v[100:103], v[60:63], v[96:99]
	v_mfma_f32_16x16x32_bf16 v[100:103], v[120:123], v[48:51], v[144:147]
	v_mfma_f32_16x16x32_bf16 v[96:99], v[120:123], v[64:67], v[96:99]
	v_mfma_f32_16x16x32_bf16 v[100:103], v[124:127], v[52:55], v[100:103]
	v_mfma_f32_16x16x32_bf16 v[96:99], v[124:127], v[68:71], v[96:99]
	v_mfma_f32_16x16x32_bf16 v[100:103], v[128:131], v[104:107], v[100:103]
	v_mfma_f32_16x16x32_bf16 v[96:99], v[128:131], v[112:115], v[96:99]
	v_mfma_f32_16x16x32_bf16 v[144:147], v[132:135], v[108:111], v[100:103]
	v_mfma_f32_16x16x32_bf16 v[96:99], v[132:135], v[116:119], v[96:99]
	s_setprio 0
	s_nop 3
	ds_read_b128 v[100:103], v156 offset:4096
	ds_read_b128 v[120:123], v157 offset:4096
	ds_read_b128 v[124:127], v158 offset:4096
	ds_read_b128 v[128:131], v159 offset:4096
	ds_read_b128 v[132:135], v235 offset:18432
	ds_read_b128 v[152:155], v236 offset:18432
	s_setprio 1
	s_waitcnt lgkmcnt(0)
	v_mfma_f32_16x16x32_bf16 v[148:151], v[100:103], v[40:43], v[136:139]
	v_mfma_f32_16x16x32_bf16 v[100:103], v[100:103], v[56:59], v[140:143]
	v_mfma_f32_16x16x32_bf16 v[148:151], v[120:123], v[44:47], v[148:151]
	v_mfma_f32_16x16x32_bf16 v[100:103], v[120:123], v[60:63], v[100:103]
	v_mfma_f32_16x16x32_bf16 v[120:123], v[124:127], v[48:51], v[148:151]
	v_mfma_f32_16x16x32_bf16 v[100:103], v[124:127], v[64:67], v[100:103]
	v_mfma_f32_16x16x32_bf16 v[120:123], v[128:131], v[52:55], v[120:123]
	v_mfma_f32_16x16x32_bf16 v[100:103], v[128:131], v[68:71], v[100:103]
	v_mfma_f32_16x16x32_bf16 v[120:123], v[132:135], v[104:107], v[120:123]
	v_mfma_f32_16x16x32_bf16 v[100:103], v[132:135], v[112:115], v[100:103]
	v_mfma_f32_16x16x32_bf16 v[148:151], v[152:155], v[108:111], v[120:123]
	v_mfma_f32_16x16x32_bf16 v[100:103], v[152:155], v[116:119], v[100:103]
	s_setprio 0
	s_nop 3
	ds_read_b128 v[120:123], v156 offset:8192
	ds_read_b128 v[124:127], v157 offset:8192
	ds_read_b128 v[128:131], v158 offset:8192
	ds_read_b128 v[132:135], v159 offset:8192
	ds_read_b128 v[152:155], v235 offset:20480
	ds_read_b128 v[156:159], v236 offset:20480
	s_setprio 1
	s_waitcnt lgkmcnt(0)
	v_mfma_f32_16x16x32_bf16 v[238:241], v[120:123], v[40:43], v[136:139]
	v_mfma_f32_16x16x32_bf16 v[120:123], v[120:123], v[56:59], v[140:143]
	v_mfma_f32_16x16x32_bf16 v[238:241], v[124:127], v[44:47], v[238:241]
	v_mfma_f32_16x16x32_bf16 v[120:123], v[124:127], v[60:63], v[120:123]
	v_mfma_f32_16x16x32_bf16 v[124:127], v[128:131], v[48:51], v[238:241]
	v_mfma_f32_16x16x32_bf16 v[120:123], v[128:131], v[64:67], v[120:123]
	v_mfma_f32_16x16x32_bf16 v[124:127], v[132:135], v[52:55], v[124:127]
	v_mfma_f32_16x16x32_bf16 v[120:123], v[132:135], v[68:71], v[120:123]
	v_mfma_f32_16x16x32_bf16 v[124:127], v[152:155], v[104:107], v[124:127]
	v_mfma_f32_16x16x32_bf16 v[120:123], v[152:155], v[112:115], v[120:123]
	v_mfma_f32_16x16x32_bf16 v[152:155], v[156:159], v[108:111], v[124:127]
	v_mfma_f32_16x16x32_bf16 v[128:131], v[156:159], v[116:119], v[120:123]
	s_setprio 0
	v_add_u32_e32 v132, s19, v225
	s_nop 3
	v_add_u32_e32 v120, v132, v227
	v_add_u32_e32 v124, v132, v228
	v_add_u32_e32 v133, v132, v229
	v_add_u32_e32 v156, v132, v230
	v_add_u32_e32 v237, v237, v226
	v_add_u32_e32 v242, v242, v226
	ds_read_b128 v[120:123], v120
	ds_read_b128 v[124:127], v124
	ds_read_b128 v[132:135], v133
	ds_read_b128 v[156:159], v156
	ds_read_b128 v[238:241], v237 offset:16384
	ds_read_b128 v[242:245], v242 offset:16384
	s_setprio 1
	s_waitcnt lgkmcnt(0)
	v_mfma_f32_16x16x32_bf16 v[136:139], v[120:123], v[40:43], v[136:139]
	v_mfma_f32_16x16x32_bf16 v[120:123], v[120:123], v[56:59], v[140:143]
	v_mfma_f32_16x16x32_bf16 v[136:139], v[124:127], v[44:47], v[136:139]
	v_mfma_f32_16x16x32_bf16 v[120:123], v[124:127], v[60:63], v[120:123]
	v_mfma_f32_16x16x32_bf16 v[124:127], v[132:135], v[48:51], v[136:139]
	v_mfma_f32_16x16x32_bf16 v[120:123], v[132:135], v[64:67], v[120:123]
	v_mfma_f32_16x16x32_bf16 v[124:127], v[156:159], v[52:55], v[124:127]
	v_mfma_f32_16x16x32_bf16 v[120:123], v[156:159], v[68:71], v[120:123]
	v_mfma_f32_16x16x32_bf16 v[104:107], v[238:241], v[104:107], v[124:127]
	v_mfma_f32_16x16x32_bf16 v[112:115], v[238:241], v[112:115], v[120:123]
	v_mfma_f32_16x16x32_bf16 v[156:159], v[242:245], v[108:111], v[104:107]
	v_mfma_f32_16x16x32_bf16 v[140:143], v[242:245], v[116:119], v[112:115]
	s_setprio 0
	s_nop 2
	ds_read_b128 v[120:123], v235 offset:24576
	ds_read_b128 v[124:127], v235 offset:26624
	ds_read_b128 v[108:111], v236 offset:24576
	ds_read_b128 v[104:107], v236 offset:26624
	ds_read_b128 v[132:135], v235 offset:28672
	ds_read_b128 v[136:139], v235 offset:30720
	ds_read_b128 v[116:119], v236 offset:28672
	ds_read_b128 v[112:115], v236 offset:30720
	v_max3_f32 v239, v144, s27, v145
	v_max3_f32 v239, v239, v146, v147
	v_max3_f32 v239, v239, v148, v149
	v_and_b32_e32 v238, 64, v208
	v_max3_f32 v239, v239, v150, v151
	v_xor_b32_e32 v237, 16, v208
	v_add_u32_e32 v238, 64, v238
	v_max3_f32 v239, v239, v152, v153
	v_cmp_lt_i32_e32 vcc, v237, v238
	v_max3_f32 v239, v239, v154, v155
	v_max3_f32 v239, v239, v156, v157
	v_cndmask_b32_e32 v237, v208, v237, vcc
	v_lshlrev_b32_e32 v237, 2, v237
	v_max3_f32 v239, v239, v158, v159
	ds_bpermute_b32 v240, v237, v239
	v_xor_b32_e32 v241, 32, v208
	v_cmp_lt_i32_e32 vcc, v241, v238
	s_cmp_eq_u32 s21, 0
	s_cselect_b64 s[38:39], -1, 0
	v_cndmask_b32_e32 v238, v208, v241, vcc
	s_waitcnt lgkmcnt(0)
	v_max_f32_e32 v240, v240, v240
	v_lshlrev_b32_e32 v238, 2, v238
	v_max_f32_e32 v239, v239, v240
	ds_bpermute_b32 v240, v238, v239
	s_waitcnt lgkmcnt(0)
	v_max_f32_e32 v240, v240, v240
	v_max_f32_e32 v239, v239, v240
	v_cmp_lt_f32_e32 vcc, s7, v239
	s_or_b64 vcc, s[38:39], vcc
	s_cbranch_vccz .LBB0_1388
	v_max_f32_e32 v240, v239, v239
	v_max_f32_e32 v240, 0, v240
	v_cndmask_b32_e64 v239, v240, v239, s[38:39]
	v_exp_f32_e64 v240, -v239
	v_add_f32_e32 v234, v234, v239
	v_sub_f32_e32 v144, v144, v239
	v_sub_f32_e32 v145, v145, v239
	v_mul_f32_e32 v195, v195, v240
	v_sub_f32_e32 v146, v146, v239
	v_sub_f32_e32 v147, v147, v239
	v_sub_f32_e32 v148, v148, v239
	v_sub_f32_e32 v149, v149, v239
	v_sub_f32_e32 v150, v150, v239
	v_sub_f32_e32 v151, v151, v239
	v_sub_f32_e32 v152, v152, v239
	v_sub_f32_e32 v153, v153, v239
	v_sub_f32_e32 v154, v154, v239
	v_sub_f32_e32 v155, v155, v239
	v_sub_f32_e32 v156, v156, v239
	v_sub_f32_e32 v157, v157, v239
	v_sub_f32_e32 v158, v158, v239
	v_sub_f32_e32 v159, v159, v239
	v_pk_mul_f32 v[94:95], v[94:95], v[240:241] op_sel_hi:[1,0]
	v_pk_mul_f32 v[92:93], v[92:93], v[240:241] op_sel_hi:[1,0]
	v_pk_mul_f32 v[90:91], v[90:91], v[240:241] op_sel_hi:[1,0]
	v_pk_mul_f32 v[88:89], v[88:89], v[240:241] op_sel_hi:[1,0]
	v_pk_mul_f32 v[86:87], v[86:87], v[240:241] op_sel_hi:[1,0]
	v_pk_mul_f32 v[84:85], v[84:85], v[240:241] op_sel_hi:[1,0]
	v_pk_mul_f32 v[82:83], v[82:83], v[240:241] op_sel_hi:[1,0]
	v_pk_mul_f32 v[80:81], v[80:81], v[240:241] op_sel_hi:[1,0]
	v_pk_mul_f32 v[78:79], v[78:79], v[240:241] op_sel_hi:[1,0]
	v_pk_mul_f32 v[76:77], v[76:77], v[240:241] op_sel_hi:[1,0]
	v_pk_mul_f32 v[74:75], v[74:75], v[240:241] op_sel_hi:[1,0]
	v_pk_mul_f32 v[72:73], v[72:73], v[240:241] op_sel_hi:[1,0]
	v_pk_mul_f32 v[38:39], v[38:39], v[240:241] op_sel_hi:[1,0]
	v_pk_mul_f32 v[36:37], v[36:37], v[240:241] op_sel_hi:[1,0]
	v_pk_mul_f32 v[34:35], v[34:35], v[240:241] op_sel_hi:[1,0]
	v_pk_mul_f32 v[32:33], v[32:33], v[240:241] op_sel_hi:[1,0]
